# prologue weight conversion: non-temporal stores for the bf16 transposed weights; mLSTM score fragments read together
# baseline (speedup 1.0000x reference)
; #define LAS __attribute__((address_space(3)))
; __device__ __forceinline__ unsigned pk2(float lo, float hi) { f32x2_t v = {lo, hi}; bf16x2_t b = __builtin_convertvector(v, bf16x2_t); return __builtin_bit_cast(unsigned, b); }
; #define LDS_WAIT() asm volatile("s_waitcnt lgkmcnt(0)" ::: "memory")
; __device__ __forceinline__ void tr_item(const float* W, int ldw, int src_c0, bf16_t* WT, int K, int n0, int k0, LAS float* scr, int lane, bool nt) {
;     const int r4 = lane >> 4, c4 = (lane & 15) * 4;
; #pragma unroll 8
;     for (int it = 0; it < 16; ++it) { const int kk = 4 * it + r4; const f32x4 v = __builtin_nontemporal_load((const f32x4*)(W + (size_t)(k0 + kk) * ldw + src_c0 + c4));
;         LAS float* d = scr + kk * 65 + c4; d[0] = v[0]; d[1] = v[1]; d[2] = v[2]; d[3] = v[3]; }
;     LDS_WAIT();
;     const int c = lane & 7;
; #pragma unroll
;     for (int j = 0; j < 8; ++j) { const int n = (lane >> 3) + 8 * j; const LAS float* s = scr + (8 * c) * 65 + n;
;         u32x4 o; o.x = pk2(s[0 * 65], s[1 * 65]); o.y = pk2(s[2 * 65], s[3 * 65]); o.z = pk2(s[4 * 65], s[5 * 65]); o.w = pk2(s[6 * 65], s[7 * 65]);
;         if (nt) __builtin_nontemporal_store(o, (u32x4*)(WT + (size_t)(n0 + n) * K + k0 + 8 * c)); else *(u32x4*)(WT + (size_t)(n0 + n) * K + k0 + 8 * c) = o; }
;     LDS_WAIT();
; }
.LBB0_15:
	v_lshl_add_u64 v[64:65], v[38:39], 0, s[44:45]
	v_lshl_add_u64 v[68:69], v[36:37], 0, s[44:45]
	v_lshl_add_u64 v[72:73], v[34:35], 0, s[44:45]
	v_lshl_add_u64 v[76:77], v[32:33], 0, s[44:45]
	v_lshl_add_u64 v[80:81], v[30:31], 0, s[44:45]
	v_lshl_add_u64 v[84:85], v[28:29], 0, s[44:45]
	v_lshl_add_u64 v[88:89], v[26:27], 0, s[44:45]
	v_lshl_add_u64 v[92:93], v[24:25], 0, s[44:45]
	global_load_dwordx4 v[64:67], v[64:65], off nt
	s_nop 0
	global_load_dwordx4 v[68:71], v[68:69], off nt
	s_nop 0
	global_load_dwordx4 v[72:75], v[72:73], off nt
	s_nop 0
	global_load_dwordx4 v[76:79], v[76:77], off nt
	s_nop 0
	global_load_dwordx4 v[80:83], v[80:81], off nt
	s_nop 0
	global_load_dwordx4 v[84:87], v[84:85], off nt
	s_nop 0
	global_load_dwordx4 v[88:91], v[88:89], off nt
	s_nop 0
	global_load_dwordx4 v[92:95], v[92:93], off nt
	s_add_u32 s44, s44, 0x40000
	s_addc_u32 s45, s45, 0
	v_add_u32_e32 v96, 0x410, v6
	v_add_u32_e32 v97, 0x418, v6
	v_add_u32_e32 v98, 0x820, v6
	v_add_u32_e32 v99, 0x828, v6
	v_add_u32_e32 v100, 0xc30, v6
	v_add_u32_e32 v101, 0xc38, v6
	v_add_u32_e32 v102, 0x1040, v6
	v_add_u32_e32 v103, 0x1048, v6
	v_add_u32_e32 v104, 0x1450, v6
	v_add_u32_e32 v105, 0x1458, v6
	v_add_u32_e32 v106, 0x1860, v6
	v_add_u32_e32 v107, 0x1868, v6
	v_add_u32_e32 v108, 0x1c70, v6
	v_add_u32_e32 v109, 0x1c78, v6
	s_cmp_lg_u32 s44, 0x80000
	s_waitcnt vmcnt(7)
	ds_write2_b32 v6, v64, v65 offset1:1
	ds_write2_b32 v6, v66, v67 offset0:2 offset1:3
	s_waitcnt vmcnt(6)
	ds_write2_b32 v96, v68, v69 offset1:1
	ds_write2_b32 v97, v70, v71 offset1:1
	s_waitcnt vmcnt(5)
	ds_write2_b32 v98, v72, v73 offset1:1
	ds_write2_b32 v99, v74, v75 offset1:1
	s_waitcnt vmcnt(4)
	ds_write2_b32 v100, v76, v77 offset1:1
	ds_write2_b32 v101, v78, v79 offset1:1
	s_waitcnt vmcnt(3)
	ds_write2_b32 v102, v80, v81 offset1:1
	ds_write2_b32 v103, v82, v83 offset1:1
	s_waitcnt vmcnt(2)
	ds_write2_b32 v104, v84, v85 offset1:1
	ds_write2_b32 v105, v86, v87 offset1:1
	s_waitcnt vmcnt(1)
	ds_write2_b32 v106, v88, v89 offset1:1
	ds_write2_b32 v107, v90, v91 offset1:1
	s_waitcnt vmcnt(0)
	ds_write2_b32 v108, v92, v93 offset1:1
	ds_write2_b32 v109, v94, v95 offset1:1
	v_add_u32_e32 v6, 0x2080, v6
	s_cbranch_scc1 .LBB0_15
	v_lshlrev_b32_e32 v6, 6, v40
	s_waitcnt lgkmcnt(0)
	v_add_u32_e32 v69, 0x400, v42
	v_and_b32_e32 v68, 0x7c0, v6
	v_lshlrev_b32_e32 v6, 1, v41
	ds_read2_b32 v[26:27], v42 offset0:65 offset1:73
	ds_read2_b32 v[28:29], v42 offset1:8
	ds_read2_b32 v[30:31], v42 offset0:130 offset1:138
	ds_read2_b32 v[32:33], v42 offset0:195 offset1:203
	ds_read2_b32 v[34:35], v69 offset0:4 offset1:12
	ds_read2_b32 v[36:37], v69 offset0:69 offset1:77
	ds_read2_b32 v[38:39], v69 offset0:134 offset1:142
	ds_read2_b32 v[40:41], v69 offset0:199 offset1:207
	v_lshl_add_u64 v[22:23], s[8:9], 0, v[22:23]
	v_lshl_add_u64 v[22:23], v[22:23], 0, v[6:7]
	v_lshlrev_b32_e32 v6, 1, v4
	v_lshl_add_u64 v[64:65], v[22:23], 0, v[6:7]
	v_or_b32_e32 v6, v68, v5
	v_lshlrev_b32_e32 v6, 14, v6
	s_waitcnt lgkmcnt(6)
	v_cvt_pk_bf16_f32 v22, v28, v26
	s_waitcnt lgkmcnt(4)
	v_cvt_pk_bf16_f32 v23, v30, v32
	s_waitcnt lgkmcnt(2)
	v_cvt_pk_bf16_f32 v24, v34, v36
	s_waitcnt lgkmcnt(0)
	v_cvt_pk_bf16_f32 v25, v38, v40
	v_lshl_add_u64 v[66:67], v[64:65], 0, v[6:7]
	global_store_dwordx4 v[66:67], v[22:25], off nt
	v_or_b32_e32 v6, v68, v43
	v_lshlrev_b32_e32 v6, 14, v6
	v_cvt_pk_bf16_f32 v22, v29, v27
	v_cvt_pk_bf16_f32 v23, v31, v33
	v_cvt_pk_bf16_f32 v24, v35, v37
	v_cvt_pk_bf16_f32 v25, v39, v41
	ds_read2_b32 v[28:29], v42 offset0:81 offset1:89
	ds_read2_b32 v[30:31], v42 offset0:16 offset1:24
	ds_read2_b32 v[32:33], v42 offset0:146 offset1:154
	ds_read2_b32 v[34:35], v42 offset0:211 offset1:219
	ds_read2_b32 v[36:37], v69 offset0:20 offset1:28
	ds_read2_b32 v[38:39], v69 offset0:85 offset1:93
	ds_read2_b32 v[40:41], v69 offset0:150 offset1:158
	ds_read2_b32 v[66:67], v69 offset0:215 offset1:223
	v_lshl_add_u64 v[26:27], v[64:65], 0, v[6:7]
	v_or_b32_e32 v6, v68, v44
	v_lshlrev_b32_e32 v6, 14, v6
	global_store_dwordx4 v[26:27], v[22:25], off nt
	v_lshl_add_u64 v[26:27], v[64:65], 0, v[6:7]
	v_or_b32_e32 v6, v68, v45
	s_waitcnt lgkmcnt(6)
	v_cvt_pk_bf16_f32 v22, v30, v28
	s_waitcnt lgkmcnt(4)
	v_cvt_pk_bf16_f32 v23, v32, v34
	s_waitcnt lgkmcnt(2)
	v_cvt_pk_bf16_f32 v24, v36, v38
	s_waitcnt lgkmcnt(0)
	v_cvt_pk_bf16_f32 v25, v40, v66
	global_store_dwordx4 v[26:27], v[22:25], off nt
	v_lshlrev_b32_e32 v6, 14, v6
	v_lshl_add_u64 v[26:27], v[64:65], 0, v[6:7]
	v_cvt_pk_bf16_f32 v22, v31, v29
	v_cvt_pk_bf16_f32 v23, v33, v35
	v_cvt_pk_bf16_f32 v24, v37, v39
	v_cvt_pk_bf16_f32 v25, v41, v67
	ds_read2_b32 v[28:29], v42 offset0:32 offset1:40
	ds_read2_b32 v[30:31], v42 offset0:97 offset1:105
	ds_read2_b32 v[32:33], v42 offset0:162 offset1:170
	ds_read2_b32 v[34:35], v42 offset0:227 offset1:235
	ds_read2_b32 v[36:37], v69 offset0:36 offset1:44
	ds_read2_b32 v[38:39], v69 offset0:101 offset1:109
	ds_read2_b32 v[40:41], v69 offset0:166 offset1:174
	ds_read2_b32 v[66:67], v69 offset0:231 offset1:239
	v_or_b32_e32 v6, v68, v46
	v_lshlrev_b32_e32 v6, 14, v6
	global_store_dwordx4 v[26:27], v[22:25], off nt
	v_lshl_add_u64 v[26:27], v[64:65], 0, v[6:7]
	v_or_b32_e32 v6, v68, v47
	s_waitcnt lgkmcnt(6)
	v_cvt_pk_bf16_f32 v22, v28, v30
	s_waitcnt lgkmcnt(4)
	v_cvt_pk_bf16_f32 v23, v32, v34
	s_waitcnt lgkmcnt(2)
	v_cvt_pk_bf16_f32 v24, v36, v38
	s_waitcnt lgkmcnt(0)
	v_cvt_pk_bf16_f32 v25, v40, v66
	global_store_dwordx4 v[26:27], v[22:25], off nt
	v_lshlrev_b32_e32 v6, 14, v6
	v_lshl_add_u64 v[26:27], v[64:65], 0, v[6:7]
	v_cvt_pk_bf16_f32 v22, v29, v31
	v_cvt_pk_bf16_f32 v23, v33, v35
	v_cvt_pk_bf16_f32 v24, v37, v39
	v_cvt_pk_bf16_f32 v25, v41, v67
	ds_read2_b32 v[28:29], v42 offset0:48 offset1:56
	ds_read2_b32 v[30:31], v42 offset0:113 offset1:121
	ds_read2_b32 v[32:33], v42 offset0:178 offset1:186
	ds_read2_b32 v[34:35], v42 offset0:243 offset1:251
	ds_read2_b32 v[36:37], v69 offset0:52 offset1:60
	ds_read2_b32 v[38:39], v69 offset0:117 offset1:125
	ds_read2_b32 v[40:41], v69 offset0:182 offset1:190
	ds_read2_b32 v[66:67], v69 offset0:247 offset1:255
	v_or_b32_e32 v6, v68, v48
	v_lshlrev_b32_e32 v6, 14, v6
	global_store_dwordx4 v[26:27], v[22:25], off nt
	v_lshl_add_u64 v[26:27], v[64:65], 0, v[6:7]
	v_or_b32_e32 v6, v68, v49
	s_waitcnt lgkmcnt(6)
	v_cvt_pk_bf16_f32 v22, v28, v30
	s_waitcnt lgkmcnt(4)
	v_cvt_pk_bf16_f32 v23, v32, v34
	s_waitcnt lgkmcnt(2)
	v_cvt_pk_bf16_f32 v24, v36, v38
	s_waitcnt lgkmcnt(0)
	v_cvt_pk_bf16_f32 v25, v40, v66
	v_lshlrev_b32_e32 v6, 14, v6
	global_store_dwordx4 v[26:27], v[22:25], off nt
	v_lshl_add_u64 v[26:27], v[64:65], 0, v[6:7]
	s_nop 0
	v_cvt_pk_bf16_f32 v22, v29, v31
	v_cvt_pk_bf16_f32 v23, v33, v35
	v_cvt_pk_bf16_f32 v24, v37, v39
	v_cvt_pk_bf16_f32 v25, v41, v67
	global_store_dwordx4 v[26:27], v[22:25], off nt
	s_waitcnt lgkmcnt(0)

; #define LAS __attribute__((address_space(3)))
; __device__ __forceinline__ unsigned pk2(float lo, float hi) { f32x2_t v = {lo, hi}; bf16x2_t b = __builtin_convertvector(v, bf16x2_t); return __builtin_bit_cast(unsigned, b); }
; #define LDS_WAIT() asm volatile("s_waitcnt lgkmcnt(0)" ::: "memory")
; __device__ __forceinline__ void tr_item(const float* W, int ldw, int src_c0, bf16_t* WT, int K, int n0, int k0, LAS float* scr, int lane, bool nt) {
;     const int r4 = lane >> 4, c4 = (lane & 15) * 4;
; #pragma unroll 8
;     for (int it = 0; it < 16; ++it) { const int kk = 4 * it + r4; const f32x4 v = __builtin_nontemporal_load((const f32x4*)(W + (size_t)(k0 + kk) * ldw + src_c0 + c4));
;         LAS float* d = scr + kk * 65 + c4; d[0] = v[0]; d[1] = v[1]; d[2] = v[2]; d[3] = v[3]; }
;     LDS_WAIT();
;     const int c = lane & 7;
; #pragma unroll
;     for (int j = 0; j < 8; ++j) { const int n = (lane >> 3) + 8 * j; const LAS float* s = scr + (8 * c) * 65 + n;
;         u32x4 o; o.x = pk2(s[0 * 65], s[1 * 65]); o.y = pk2(s[2 * 65], s[3 * 65]); o.z = pk2(s[4 * 65], s[5 * 65]); o.w = pk2(s[6 * 65], s[7 * 65]);
;         if (nt) __builtin_nontemporal_store(o, (u32x4*)(WT + (size_t)(n0 + n) * K + k0 + 8 * c)); else *(u32x4*)(WT + (size_t)(n0 + n) * K + k0 + 8 * c) = o; }
;     LDS_WAIT();
; }
.LBB0_19:
	v_lshl_add_u64 v[64:65], v[38:39], 0, s[44:45]
	v_lshl_add_u64 v[68:69], v[36:37], 0, s[44:45]
	v_lshl_add_u64 v[72:73], v[34:35], 0, s[44:45]
	v_lshl_add_u64 v[76:77], v[32:33], 0, s[44:45]
	v_lshl_add_u64 v[80:81], v[30:31], 0, s[44:45]
	v_lshl_add_u64 v[84:85], v[28:29], 0, s[44:45]
	v_lshl_add_u64 v[88:89], v[26:27], 0, s[44:45]
	v_lshl_add_u64 v[92:93], v[24:25], 0, s[44:45]
	global_load_dwordx4 v[64:67], v[64:65], off nt
	s_nop 0
	global_load_dwordx4 v[68:71], v[68:69], off nt
	s_nop 0
	global_load_dwordx4 v[72:75], v[72:73], off nt
	s_nop 0
	global_load_dwordx4 v[76:79], v[76:77], off nt
	s_nop 0
	global_load_dwordx4 v[80:83], v[80:81], off nt
	s_nop 0
	global_load_dwordx4 v[84:87], v[84:85], off nt
	s_nop 0
	global_load_dwordx4 v[88:91], v[88:89], off nt
	s_nop 0
	global_load_dwordx4 v[92:95], v[92:93], off nt
	s_add_u32 s44, s44, 0x100000
	s_addc_u32 s45, s45, 0
	v_add_u32_e32 v96, 0x410, v6
	v_add_u32_e32 v97, 0x418, v6
	v_add_u32_e32 v98, 0x820, v6
	v_add_u32_e32 v99, 0x828, v6
	v_add_u32_e32 v100, 0xc30, v6
	v_add_u32_e32 v101, 0xc38, v6
	v_add_u32_e32 v102, 0x1040, v6
	v_add_u32_e32 v103, 0x1048, v6
	v_add_u32_e32 v104, 0x1450, v6
	v_add_u32_e32 v105, 0x1458, v6
	v_add_u32_e32 v106, 0x1860, v6
	v_add_u32_e32 v107, 0x1868, v6
	v_add_u32_e32 v108, 0x1c70, v6
	v_add_u32_e32 v109, 0x1c78, v6
	s_cmp_lg_u32 s44, 0x200000
	s_waitcnt vmcnt(7)
	ds_write2_b32 v6, v64, v65 offset1:1
	ds_write2_b32 v6, v66, v67 offset0:2 offset1:3
	s_waitcnt vmcnt(6)
	ds_write2_b32 v96, v68, v69 offset1:1
	ds_write2_b32 v97, v70, v71 offset1:1
	s_waitcnt vmcnt(5)
	ds_write2_b32 v98, v72, v73 offset1:1
	ds_write2_b32 v99, v74, v75 offset1:1
	s_waitcnt vmcnt(4)
	ds_write2_b32 v100, v76, v77 offset1:1
	ds_write2_b32 v101, v78, v79 offset1:1
	s_waitcnt vmcnt(3)
	ds_write2_b32 v102, v80, v81 offset1:1
	ds_write2_b32 v103, v82, v83 offset1:1
	s_waitcnt vmcnt(2)
	ds_write2_b32 v104, v84, v85 offset1:1
	ds_write2_b32 v105, v86, v87 offset1:1
	s_waitcnt vmcnt(1)
	ds_write2_b32 v106, v88, v89 offset1:1
	ds_write2_b32 v107, v90, v91 offset1:1
	s_waitcnt vmcnt(0)
	ds_write2_b32 v108, v92, v93 offset1:1
	ds_write2_b32 v109, v94, v95 offset1:1
	v_add_u32_e32 v6, 0x2080, v6
	s_cbranch_scc1 .LBB0_19
	v_lshlrev_b32_e32 v6, 6, v40
	s_waitcnt lgkmcnt(0)
	v_add_u32_e32 v69, 0x400, v42
	v_and_b32_e32 v68, 0x1fc0, v6
	v_lshlrev_b32_e32 v6, 1, v41
	ds_read2_b32 v[26:27], v42 offset0:65 offset1:73
	ds_read2_b32 v[28:29], v42 offset1:8
	ds_read2_b32 v[30:31], v42 offset0:130 offset1:138
	ds_read2_b32 v[32:33], v42 offset0:195 offset1:203
	ds_read2_b32 v[34:35], v69 offset0:4 offset1:12
	ds_read2_b32 v[36:37], v69 offset0:69 offset1:77
	ds_read2_b32 v[38:39], v69 offset0:134 offset1:142
	ds_read2_b32 v[40:41], v69 offset0:199 offset1:207
	v_lshl_add_u64 v[22:23], s[10:11], 0, v[22:23]
	v_lshl_add_u64 v[22:23], v[22:23], 0, v[6:7]
	v_lshlrev_b32_e32 v6, 1, v4
	v_lshl_add_u64 v[64:65], v[22:23], 0, v[6:7]
	v_or_b32_e32 v6, v68, v5
	v_lshlrev_b32_e32 v6, 12, v6
	s_waitcnt lgkmcnt(6)
	v_cvt_pk_bf16_f32 v22, v28, v26
	s_waitcnt lgkmcnt(4)
	v_cvt_pk_bf16_f32 v23, v30, v32
	s_waitcnt lgkmcnt(2)
	v_cvt_pk_bf16_f32 v24, v34, v36
	s_waitcnt lgkmcnt(0)
	v_cvt_pk_bf16_f32 v25, v38, v40
	v_lshl_add_u64 v[66:67], v[64:65], 0, v[6:7]
	global_store_dwordx4 v[66:67], v[22:25], off nt
	v_or_b32_e32 v6, v68, v43
	v_lshlrev_b32_e32 v6, 12, v6
	v_cvt_pk_bf16_f32 v22, v29, v27
	v_cvt_pk_bf16_f32 v23, v31, v33
	v_cvt_pk_bf16_f32 v24, v35, v37
	v_cvt_pk_bf16_f32 v25, v39, v41
	ds_read2_b32 v[28:29], v42 offset0:81 offset1:89
	ds_read2_b32 v[30:31], v42 offset0:16 offset1:24
	ds_read2_b32 v[32:33], v42 offset0:146 offset1:154
	ds_read2_b32 v[34:35], v42 offset0:211 offset1:219
	ds_read2_b32 v[36:37], v69 offset0:20 offset1:28
	ds_read2_b32 v[38:39], v69 offset0:85 offset1:93
	ds_read2_b32 v[40:41], v69 offset0:150 offset1:158
	ds_read2_b32 v[66:67], v69 offset0:215 offset1:223
	v_lshl_add_u64 v[26:27], v[64:65], 0, v[6:7]
	v_or_b32_e32 v6, v68, v44
	v_lshlrev_b32_e32 v6, 12, v6
	global_store_dwordx4 v[26:27], v[22:25], off nt
	v_lshl_add_u64 v[26:27], v[64:65], 0, v[6:7]
	v_or_b32_e32 v6, v68, v45
	s_waitcnt lgkmcnt(6)
	v_cvt_pk_bf16_f32 v22, v30, v28
	s_waitcnt lgkmcnt(4)
	v_cvt_pk_bf16_f32 v23, v32, v34
	s_waitcnt lgkmcnt(2)
	v_cvt_pk_bf16_f32 v24, v36, v38
	s_waitcnt lgkmcnt(0)
	v_cvt_pk_bf16_f32 v25, v40, v66
	global_store_dwordx4 v[26:27], v[22:25], off nt
	v_lshlrev_b32_e32 v6, 12, v6
	v_lshl_add_u64 v[26:27], v[64:65], 0, v[6:7]
	v_cvt_pk_bf16_f32 v22, v31, v29
	v_cvt_pk_bf16_f32 v23, v33, v35
	v_cvt_pk_bf16_f32 v24, v37, v39
	v_cvt_pk_bf16_f32 v25, v41, v67
	ds_read2_b32 v[28:29], v42 offset0:32 offset1:40
	ds_read2_b32 v[30:31], v42 offset0:97 offset1:105
	ds_read2_b32 v[32:33], v42 offset0:162 offset1:170
	ds_read2_b32 v[34:35], v42 offset0:227 offset1:235
	ds_read2_b32 v[36:37], v69 offset0:36 offset1:44
	ds_read2_b32 v[38:39], v69 offset0:101 offset1:109
	ds_read2_b32 v[40:41], v69 offset0:166 offset1:174
	ds_read2_b32 v[66:67], v69 offset0:231 offset1:239
	v_or_b32_e32 v6, v68, v46
	v_lshlrev_b32_e32 v6, 12, v6
	global_store_dwordx4 v[26:27], v[22:25], off nt
	v_lshl_add_u64 v[26:27], v[64:65], 0, v[6:7]
	v_or_b32_e32 v6, v68, v47
	s_waitcnt lgkmcnt(6)
	v_cvt_pk_bf16_f32 v22, v28, v30
	s_waitcnt lgkmcnt(4)
	v_cvt_pk_bf16_f32 v23, v32, v34
	s_waitcnt lgkmcnt(2)
	v_cvt_pk_bf16_f32 v24, v36, v38
	s_waitcnt lgkmcnt(0)
	v_cvt_pk_bf16_f32 v25, v40, v66
	global_store_dwordx4 v[26:27], v[22:25], off nt
	v_lshlrev_b32_e32 v6, 12, v6
	v_lshl_add_u64 v[26:27], v[64:65], 0, v[6:7]
	v_cvt_pk_bf16_f32 v22, v29, v31
	v_cvt_pk_bf16_f32 v23, v33, v35
	v_cvt_pk_bf16_f32 v24, v37, v39
	v_cvt_pk_bf16_f32 v25, v41, v67
	ds_read2_b32 v[28:29], v42 offset0:48 offset1:56
	ds_read2_b32 v[30:31], v42 offset0:113 offset1:121
	ds_read2_b32 v[32:33], v42 offset0:178 offset1:186
	ds_read2_b32 v[34:35], v42 offset0:243 offset1:251
	ds_read2_b32 v[36:37], v69 offset0:52 offset1:60
	ds_read2_b32 v[38:39], v69 offset0:117 offset1:125
	ds_read2_b32 v[40:41], v69 offset0:182 offset1:190
	ds_read2_b32 v[66:67], v69 offset0:247 offset1:255
	v_or_b32_e32 v6, v68, v48
	v_lshlrev_b32_e32 v6, 12, v6
	global_store_dwordx4 v[26:27], v[22:25], off nt
	v_lshl_add_u64 v[26:27], v[64:65], 0, v[6:7]
	v_or_b32_e32 v6, v68, v49
	s_waitcnt lgkmcnt(6)
	v_cvt_pk_bf16_f32 v22, v28, v30
	s_waitcnt lgkmcnt(4)
	v_cvt_pk_bf16_f32 v23, v32, v34
	s_waitcnt lgkmcnt(2)
	v_cvt_pk_bf16_f32 v24, v36, v38
	s_waitcnt lgkmcnt(0)
	v_cvt_pk_bf16_f32 v25, v40, v66
	v_lshlrev_b32_e32 v6, 12, v6
	global_store_dwordx4 v[26:27], v[22:25], off nt
	v_lshl_add_u64 v[26:27], v[64:65], 0, v[6:7]
	s_nop 0
	v_cvt_pk_bf16_f32 v22, v29, v31
	v_cvt_pk_bf16_f32 v23, v33, v35
	v_cvt_pk_bf16_f32 v24, v37, v39
	v_cvt_pk_bf16_f32 v25, v41, v67
	global_store_dwordx4 v[26:27], v[22:25], off nt
	s_waitcnt lgkmcnt(0)

; #define LAS __attribute__((address_space(3)))
; __device__ __forceinline__ unsigned pk2(float lo, float hi) { f32x2_t v = {lo, hi}; bf16x2_t b = __builtin_convertvector(v, bf16x2_t); return __builtin_bit_cast(unsigned, b); }
; #define LDS_WAIT() asm volatile("s_waitcnt lgkmcnt(0)" ::: "memory")
; __device__ __forceinline__ void tr_item(const float* W, int ldw, int src_c0, bf16_t* WT, int K, int n0, int k0, LAS float* scr, int lane, bool nt) {
;     const int r4 = lane >> 4, c4 = (lane & 15) * 4;
; #pragma unroll 8
;     for (int it = 0; it < 16; ++it) { const int kk = 4 * it + r4; const f32x4 v = __builtin_nontemporal_load((const f32x4*)(W + (size_t)(k0 + kk) * ldw + src_c0 + c4));
;         LAS float* d = scr + kk * 65 + c4; d[0] = v[0]; d[1] = v[1]; d[2] = v[2]; d[3] = v[3]; }
;     LDS_WAIT();
;     const int c = lane & 7;
; #pragma unroll
;     for (int j = 0; j < 8; ++j) { const int n = (lane >> 3) + 8 * j; const LAS float* s = scr + (8 * c) * 65 + n;
;         u32x4 o; o.x = pk2(s[0 * 65], s[1 * 65]); o.y = pk2(s[2 * 65], s[3 * 65]); o.z = pk2(s[4 * 65], s[5 * 65]); o.w = pk2(s[6 * 65], s[7 * 65]);
;         if (nt) __builtin_nontemporal_store(o, (u32x4*)(WT + (size_t)(n0 + n) * K + k0 + 8 * c)); else *(u32x4*)(WT + (size_t)(n0 + n) * K + k0 + 8 * c) = o; }
;     LDS_WAIT();
; }
.LBB0_24:
	v_lshl_add_u64 v[64:65], v[38:39], 0, s[42:43]
	v_lshl_add_u64 v[68:69], v[36:37], 0, s[42:43]
	v_lshl_add_u64 v[72:73], v[34:35], 0, s[42:43]
	v_lshl_add_u64 v[76:77], v[32:33], 0, s[42:43]
	v_lshl_add_u64 v[80:81], v[30:31], 0, s[42:43]
	v_lshl_add_u64 v[84:85], v[28:29], 0, s[42:43]
	v_lshl_add_u64 v[88:89], v[26:27], 0, s[42:43]
	v_lshl_add_u64 v[92:93], v[24:25], 0, s[42:43]
	global_load_dwordx4 v[64:67], v[64:65], off nt
	s_nop 0
	global_load_dwordx4 v[68:71], v[68:69], off nt
	s_nop 0
	global_load_dwordx4 v[72:75], v[72:73], off nt
	s_nop 0
	global_load_dwordx4 v[76:79], v[76:77], off nt
	s_nop 0
	global_load_dwordx4 v[80:83], v[80:81], off nt
	s_nop 0
	global_load_dwordx4 v[84:87], v[84:85], off nt
	s_nop 0
	global_load_dwordx4 v[88:91], v[88:89], off nt
	s_nop 0
	global_load_dwordx4 v[92:95], v[92:93], off nt
	s_add_u32 s42, s42, 0x40000
	s_addc_u32 s43, s43, 0
	v_add_u32_e32 v96, 0x410, v6
	v_add_u32_e32 v97, 0x418, v6
	v_add_u32_e32 v98, 0x820, v6
	v_add_u32_e32 v99, 0x828, v6
	v_add_u32_e32 v100, 0xc30, v6
	v_add_u32_e32 v101, 0xc38, v6
	v_add_u32_e32 v102, 0x1040, v6
	v_add_u32_e32 v103, 0x1048, v6
	v_add_u32_e32 v104, 0x1450, v6
	v_add_u32_e32 v105, 0x1458, v6
	v_add_u32_e32 v106, 0x1860, v6
	v_add_u32_e32 v107, 0x1868, v6
	v_add_u32_e32 v108, 0x1c70, v6
	v_add_u32_e32 v109, 0x1c78, v6
	s_cmp_lg_u32 s42, 0x80000
	s_waitcnt vmcnt(7)
	ds_write2_b32 v6, v64, v65 offset1:1
	ds_write2_b32 v6, v66, v67 offset0:2 offset1:3
	s_waitcnt vmcnt(6)
	ds_write2_b32 v96, v68, v69 offset1:1
	ds_write2_b32 v97, v70, v71 offset1:1
	s_waitcnt vmcnt(5)
	ds_write2_b32 v98, v72, v73 offset1:1
	ds_write2_b32 v99, v74, v75 offset1:1
	s_waitcnt vmcnt(4)
	ds_write2_b32 v100, v76, v77 offset1:1
	ds_write2_b32 v101, v78, v79 offset1:1
	s_waitcnt vmcnt(3)
	ds_write2_b32 v102, v80, v81 offset1:1
	ds_write2_b32 v103, v82, v83 offset1:1
	s_waitcnt vmcnt(2)
	ds_write2_b32 v104, v84, v85 offset1:1
	ds_write2_b32 v105, v86, v87 offset1:1
	s_waitcnt vmcnt(1)
	ds_write2_b32 v106, v88, v89 offset1:1
	ds_write2_b32 v107, v90, v91 offset1:1
	s_waitcnt vmcnt(0)
	ds_write2_b32 v108, v92, v93 offset1:1
	ds_write2_b32 v109, v94, v95 offset1:1
	v_add_u32_e32 v6, 0x2080, v6
	s_cbranch_scc1 .LBB0_24
	v_lshlrev_b32_e32 v6, 6, v40
	s_waitcnt lgkmcnt(0)
	v_add_u32_e32 v69, 0x400, v42
	v_lshlrev_b64 v[22:23], 23, v[22:23]
	v_and_b32_e32 v68, 0x7c0, v6
	v_lshlrev_b32_e32 v6, 1, v41
	ds_read2_b32 v[26:27], v42 offset0:65 offset1:73
	ds_read2_b32 v[28:29], v42 offset1:8
	ds_read2_b32 v[30:31], v42 offset0:130 offset1:138
	ds_read2_b32 v[32:33], v42 offset0:195 offset1:203
	ds_read2_b32 v[34:35], v69 offset0:4 offset1:12
	ds_read2_b32 v[36:37], v69 offset0:69 offset1:77
	ds_read2_b32 v[38:39], v69 offset0:134 offset1:142
	ds_read2_b32 v[40:41], v69 offset0:199 offset1:207
	v_lshl_add_u64 v[22:23], s[16:17], 0, v[22:23]
	v_lshl_add_u64 v[22:23], v[22:23], 0, v[6:7]
	v_lshlrev_b32_e32 v6, 1, v4
	v_lshl_add_u64 v[64:65], v[22:23], 0, v[6:7]
	v_or_b32_e32 v6, v68, v5
	v_lshlrev_b32_e32 v6, 12, v6
	s_waitcnt lgkmcnt(6)
	v_cvt_pk_bf16_f32 v22, v28, v26
	s_waitcnt lgkmcnt(4)
	v_cvt_pk_bf16_f32 v23, v30, v32
	s_waitcnt lgkmcnt(2)
	v_cvt_pk_bf16_f32 v24, v34, v36
	s_waitcnt lgkmcnt(0)
	v_cvt_pk_bf16_f32 v25, v38, v40
	v_lshl_add_u64 v[66:67], v[64:65], 0, v[6:7]
	global_store_dwordx4 v[66:67], v[22:25], off nt
	v_or_b32_e32 v6, v68, v43
	v_lshlrev_b32_e32 v6, 12, v6
	v_cvt_pk_bf16_f32 v22, v29, v27
	v_cvt_pk_bf16_f32 v23, v31, v33
	v_cvt_pk_bf16_f32 v24, v35, v37
	v_cvt_pk_bf16_f32 v25, v39, v41
	ds_read2_b32 v[28:29], v42 offset0:81 offset1:89
	ds_read2_b32 v[30:31], v42 offset0:16 offset1:24
	ds_read2_b32 v[32:33], v42 offset0:146 offset1:154
	ds_read2_b32 v[34:35], v42 offset0:211 offset1:219
	ds_read2_b32 v[36:37], v69 offset0:20 offset1:28
	ds_read2_b32 v[38:39], v69 offset0:85 offset1:93
	ds_read2_b32 v[40:41], v69 offset0:150 offset1:158
	ds_read2_b32 v[66:67], v69 offset0:215 offset1:223
	v_lshl_add_u64 v[26:27], v[64:65], 0, v[6:7]
	v_or_b32_e32 v6, v68, v44
	v_lshlrev_b32_e32 v6, 12, v6
	global_store_dwordx4 v[26:27], v[22:25], off nt
	v_lshl_add_u64 v[26:27], v[64:65], 0, v[6:7]
	v_or_b32_e32 v6, v68, v45
	s_waitcnt lgkmcnt(6)
	v_cvt_pk_bf16_f32 v22, v30, v28
	s_waitcnt lgkmcnt(4)
	v_cvt_pk_bf16_f32 v23, v32, v34
	s_waitcnt lgkmcnt(2)
	v_cvt_pk_bf16_f32 v24, v36, v38
	s_waitcnt lgkmcnt(0)
	v_cvt_pk_bf16_f32 v25, v40, v66
	global_store_dwordx4 v[26:27], v[22:25], off nt
	v_lshlrev_b32_e32 v6, 12, v6
	v_lshl_add_u64 v[26:27], v[64:65], 0, v[6:7]
	v_cvt_pk_bf16_f32 v22, v31, v29
	v_cvt_pk_bf16_f32 v23, v33, v35
	v_cvt_pk_bf16_f32 v24, v37, v39
	v_cvt_pk_bf16_f32 v25, v41, v67
	ds_read2_b32 v[28:29], v42 offset0:32 offset1:40
	ds_read2_b32 v[30:31], v42 offset0:97 offset1:105
	ds_read2_b32 v[32:33], v42 offset0:162 offset1:170
	ds_read2_b32 v[34:35], v42 offset0:227 offset1:235
	ds_read2_b32 v[36:37], v69 offset0:36 offset1:44
	ds_read2_b32 v[38:39], v69 offset0:101 offset1:109
	ds_read2_b32 v[40:41], v69 offset0:166 offset1:174
	ds_read2_b32 v[66:67], v69 offset0:231 offset1:239
	v_or_b32_e32 v6, v68, v46
	v_lshlrev_b32_e32 v6, 12, v6
	global_store_dwordx4 v[26:27], v[22:25], off nt
	v_lshl_add_u64 v[26:27], v[64:65], 0, v[6:7]
	v_or_b32_e32 v6, v68, v47
	s_waitcnt lgkmcnt(6)
	v_cvt_pk_bf16_f32 v22, v28, v30
	s_waitcnt lgkmcnt(4)
	v_cvt_pk_bf16_f32 v23, v32, v34
	s_waitcnt lgkmcnt(2)
	v_cvt_pk_bf16_f32 v24, v36, v38
	s_waitcnt lgkmcnt(0)
	v_cvt_pk_bf16_f32 v25, v40, v66
	global_store_dwordx4 v[26:27], v[22:25], off nt
	v_lshlrev_b32_e32 v6, 12, v6
	v_lshl_add_u64 v[26:27], v[64:65], 0, v[6:7]
	v_cvt_pk_bf16_f32 v22, v29, v31
	v_cvt_pk_bf16_f32 v23, v33, v35
	v_cvt_pk_bf16_f32 v24, v37, v39
	v_cvt_pk_bf16_f32 v25, v41, v67
	ds_read2_b32 v[28:29], v42 offset0:48 offset1:56
	ds_read2_b32 v[30:31], v42 offset0:113 offset1:121
	ds_read2_b32 v[32:33], v42 offset0:178 offset1:186
	ds_read2_b32 v[34:35], v42 offset0:243 offset1:251
	ds_read2_b32 v[36:37], v69 offset0:52 offset1:60
	ds_read2_b32 v[38:39], v69 offset0:117 offset1:125
	ds_read2_b32 v[40:41], v69 offset0:182 offset1:190
	ds_read2_b32 v[66:67], v69 offset0:247 offset1:255
	v_or_b32_e32 v6, v68, v48
	v_lshlrev_b32_e32 v6, 12, v6
	global_store_dwordx4 v[26:27], v[22:25], off nt
	v_lshl_add_u64 v[26:27], v[64:65], 0, v[6:7]
	v_or_b32_e32 v6, v68, v49
	s_waitcnt lgkmcnt(6)
	v_cvt_pk_bf16_f32 v22, v28, v30
	s_waitcnt lgkmcnt(4)
	v_cvt_pk_bf16_f32 v23, v32, v34
	s_waitcnt lgkmcnt(2)
	v_cvt_pk_bf16_f32 v24, v36, v38
	s_waitcnt lgkmcnt(0)
	v_cvt_pk_bf16_f32 v25, v40, v66
	v_lshlrev_b32_e32 v6, 12, v6
	global_store_dwordx4 v[26:27], v[22:25], off nt
	v_lshl_add_u64 v[26:27], v[64:65], 0, v[6:7]
	s_nop 0
	v_cvt_pk_bf16_f32 v22, v29, v31
	v_cvt_pk_bf16_f32 v23, v33, v35
	v_cvt_pk_bf16_f32 v24, v37, v39
	v_cvt_pk_bf16_f32 v25, v41, v67
	global_store_dwordx4 v[26:27], v[22:25], off nt
	s_waitcnt lgkmcnt(0)

; #define LAS __attribute__((address_space(3)))
; __device__ __forceinline__ unsigned pk2(float lo, float hi) { f32x2_t v = {lo, hi}; bf16x2_t b = __builtin_convertvector(v, bf16x2_t); return __builtin_bit_cast(unsigned, b); }
; #define LDS_WAIT() asm volatile("s_waitcnt lgkmcnt(0)" ::: "memory")
; __device__ __forceinline__ void tr_item(const float* W, int ldw, int src_c0, bf16_t* WT, int K, int n0, int k0, LAS float* scr, int lane, bool nt) {
;     const int r4 = lane >> 4, c4 = (lane & 15) * 4;
; #pragma unroll 8
;     for (int it = 0; it < 16; ++it) { const int kk = 4 * it + r4; const f32x4 v = __builtin_nontemporal_load((const f32x4*)(W + (size_t)(k0 + kk) * ldw + src_c0 + c4));
;         LAS float* d = scr + kk * 65 + c4; d[0] = v[0]; d[1] = v[1]; d[2] = v[2]; d[3] = v[3]; }
;     LDS_WAIT();
;     const int c = lane & 7;
; #pragma unroll
;     for (int j = 0; j < 8; ++j) { const int n = (lane >> 3) + 8 * j; const LAS float* s = scr + (8 * c) * 65 + n;
;         u32x4 o; o.x = pk2(s[0 * 65], s[1 * 65]); o.y = pk2(s[2 * 65], s[3 * 65]); o.z = pk2(s[4 * 65], s[5 * 65]); o.w = pk2(s[6 * 65], s[7 * 65]);
;         if (nt) __builtin_nontemporal_store(o, (u32x4*)(WT + (size_t)(n0 + n) * K + k0 + 8 * c)); else *(u32x4*)(WT + (size_t)(n0 + n) * K + k0 + 8 * c) = o; }
;     LDS_WAIT();
; }
.LBB0_29:
	v_lshl_add_u64 v[64:65], v[38:39], 0, s[40:41]
	v_lshl_add_u64 v[68:69], v[36:37], 0, s[40:41]
	v_lshl_add_u64 v[72:73], v[34:35], 0, s[40:41]
	v_lshl_add_u64 v[76:77], v[32:33], 0, s[40:41]
	v_lshl_add_u64 v[80:81], v[30:31], 0, s[40:41]
	v_lshl_add_u64 v[84:85], v[28:29], 0, s[40:41]
	v_lshl_add_u64 v[88:89], v[26:27], 0, s[40:41]
	v_lshl_add_u64 v[92:93], v[24:25], 0, s[40:41]
	global_load_dwordx4 v[64:67], v[64:65], off nt
	s_nop 0
	global_load_dwordx4 v[68:71], v[68:69], off nt
	s_nop 0
	global_load_dwordx4 v[72:75], v[72:73], off nt
	s_nop 0
	global_load_dwordx4 v[76:79], v[76:77], off nt
	s_nop 0
	global_load_dwordx4 v[80:83], v[80:81], off nt
	s_nop 0
	global_load_dwordx4 v[84:87], v[84:85], off nt
	s_nop 0
	global_load_dwordx4 v[88:91], v[88:89], off nt
	s_nop 0
	global_load_dwordx4 v[92:95], v[92:93], off nt
	s_add_u32 s40, s40, 0x40000
	s_addc_u32 s41, s41, 0
	v_add_u32_e32 v96, 0x410, v6
	v_add_u32_e32 v97, 0x418, v6
	v_add_u32_e32 v98, 0x820, v6
	v_add_u32_e32 v99, 0x828, v6
	v_add_u32_e32 v100, 0xc30, v6
	v_add_u32_e32 v101, 0xc38, v6
	v_add_u32_e32 v102, 0x1040, v6
	v_add_u32_e32 v103, 0x1048, v6
	v_add_u32_e32 v104, 0x1450, v6
	v_add_u32_e32 v105, 0x1458, v6
	v_add_u32_e32 v106, 0x1860, v6
	v_add_u32_e32 v107, 0x1868, v6
	v_add_u32_e32 v108, 0x1c70, v6
	v_add_u32_e32 v109, 0x1c78, v6
	s_cmp_lg_u32 s40, 0x80000
	s_waitcnt vmcnt(7)
	ds_write2_b32 v6, v64, v65 offset1:1
	ds_write2_b32 v6, v66, v67 offset0:2 offset1:3
	s_waitcnt vmcnt(6)
	ds_write2_b32 v96, v68, v69 offset1:1
	ds_write2_b32 v97, v70, v71 offset1:1
	s_waitcnt vmcnt(5)
	ds_write2_b32 v98, v72, v73 offset1:1
	ds_write2_b32 v99, v74, v75 offset1:1
	s_waitcnt vmcnt(4)
	ds_write2_b32 v100, v76, v77 offset1:1
	ds_write2_b32 v101, v78, v79 offset1:1
	s_waitcnt vmcnt(3)
	ds_write2_b32 v102, v80, v81 offset1:1
	ds_write2_b32 v103, v82, v83 offset1:1
	s_waitcnt vmcnt(2)
	ds_write2_b32 v104, v84, v85 offset1:1
	ds_write2_b32 v105, v86, v87 offset1:1
	s_waitcnt vmcnt(1)
	ds_write2_b32 v106, v88, v89 offset1:1
	ds_write2_b32 v107, v90, v91 offset1:1
	s_waitcnt vmcnt(0)
	ds_write2_b32 v108, v92, v93 offset1:1
	ds_write2_b32 v109, v94, v95 offset1:1
	v_add_u32_e32 v6, 0x2080, v6
	s_cbranch_scc1 .LBB0_29
	v_lshlrev_b32_e32 v6, 6, v40
	s_waitcnt lgkmcnt(0)
	v_add_u32_e32 v69, 0x400, v42
	v_lshlrev_b64 v[22:23], 22, v[22:23]
	v_and_b32_e32 v68, 0x7c0, v6
	v_lshlrev_b32_e32 v6, 1, v41
	ds_read2_b32 v[26:27], v42 offset0:65 offset1:73
	ds_read2_b32 v[28:29], v42 offset1:8
	ds_read2_b32 v[30:31], v42 offset0:130 offset1:138
	ds_read2_b32 v[32:33], v42 offset0:195 offset1:203
	ds_read2_b32 v[34:35], v69 offset0:4 offset1:12
	ds_read2_b32 v[36:37], v69 offset0:69 offset1:77
	ds_read2_b32 v[38:39], v69 offset0:134 offset1:142
	ds_read2_b32 v[40:41], v69 offset0:199 offset1:207
	v_lshl_add_u64 v[22:23], s[18:19], 0, v[22:23]
	v_lshl_add_u64 v[22:23], v[22:23], 0, v[6:7]
	v_lshlrev_b32_e32 v6, 1, v4
	v_lshl_add_u64 v[64:65], v[22:23], 0, v[6:7]
	v_or_b32_e32 v6, v68, v5
	v_lshlrev_b32_e32 v6, 11, v6
	s_waitcnt lgkmcnt(6)
	v_cvt_pk_bf16_f32 v22, v28, v26
	s_waitcnt lgkmcnt(4)
	v_cvt_pk_bf16_f32 v23, v30, v32
	s_waitcnt lgkmcnt(2)
	v_cvt_pk_bf16_f32 v24, v34, v36
	s_waitcnt lgkmcnt(0)
	v_cvt_pk_bf16_f32 v25, v38, v40
	v_lshl_add_u64 v[66:67], v[64:65], 0, v[6:7]
	global_store_dwordx4 v[66:67], v[22:25], off nt
	v_or_b32_e32 v6, v68, v43
	v_lshlrev_b32_e32 v6, 11, v6
	v_cvt_pk_bf16_f32 v22, v29, v27
	v_cvt_pk_bf16_f32 v23, v31, v33
	v_cvt_pk_bf16_f32 v24, v35, v37
	v_cvt_pk_bf16_f32 v25, v39, v41
	ds_read2_b32 v[28:29], v42 offset0:81 offset1:89
	ds_read2_b32 v[30:31], v42 offset0:16 offset1:24
	ds_read2_b32 v[32:33], v42 offset0:146 offset1:154
	ds_read2_b32 v[34:35], v42 offset0:211 offset1:219
	ds_read2_b32 v[36:37], v69 offset0:20 offset1:28
	ds_read2_b32 v[38:39], v69 offset0:85 offset1:93
	ds_read2_b32 v[40:41], v69 offset0:150 offset1:158
	ds_read2_b32 v[66:67], v69 offset0:215 offset1:223
	v_lshl_add_u64 v[26:27], v[64:65], 0, v[6:7]
	v_or_b32_e32 v6, v68, v44
	v_lshlrev_b32_e32 v6, 11, v6
	global_store_dwordx4 v[26:27], v[22:25], off nt
	v_lshl_add_u64 v[26:27], v[64:65], 0, v[6:7]
	v_or_b32_e32 v6, v68, v45
	s_waitcnt lgkmcnt(6)
	v_cvt_pk_bf16_f32 v22, v30, v28
	s_waitcnt lgkmcnt(4)
	v_cvt_pk_bf16_f32 v23, v32, v34
	s_waitcnt lgkmcnt(2)
	v_cvt_pk_bf16_f32 v24, v36, v38
	s_waitcnt lgkmcnt(0)
	v_cvt_pk_bf16_f32 v25, v40, v66
	global_store_dwordx4 v[26:27], v[22:25], off nt
	v_lshlrev_b32_e32 v6, 11, v6
	v_lshl_add_u64 v[26:27], v[64:65], 0, v[6:7]
	v_cvt_pk_bf16_f32 v22, v31, v29
	v_cvt_pk_bf16_f32 v23, v33, v35
	v_cvt_pk_bf16_f32 v24, v37, v39
	v_cvt_pk_bf16_f32 v25, v41, v67
	ds_read2_b32 v[28:29], v42 offset0:32 offset1:40
	ds_read2_b32 v[30:31], v42 offset0:97 offset1:105
	ds_read2_b32 v[32:33], v42 offset0:162 offset1:170
	ds_read2_b32 v[34:35], v42 offset0:227 offset1:235
	ds_read2_b32 v[36:37], v69 offset0:36 offset1:44
	ds_read2_b32 v[38:39], v69 offset0:101 offset1:109
	ds_read2_b32 v[40:41], v69 offset0:166 offset1:174
	ds_read2_b32 v[66:67], v69 offset0:231 offset1:239
	v_or_b32_e32 v6, v68, v46
	v_lshlrev_b32_e32 v6, 11, v6
	global_store_dwordx4 v[26:27], v[22:25], off nt
	v_lshl_add_u64 v[26:27], v[64:65], 0, v[6:7]
	v_or_b32_e32 v6, v68, v47
	s_waitcnt lgkmcnt(6)
	v_cvt_pk_bf16_f32 v22, v28, v30
	s_waitcnt lgkmcnt(4)
	v_cvt_pk_bf16_f32 v23, v32, v34
	s_waitcnt lgkmcnt(2)
	v_cvt_pk_bf16_f32 v24, v36, v38
	s_waitcnt lgkmcnt(0)
	v_cvt_pk_bf16_f32 v25, v40, v66
	global_store_dwordx4 v[26:27], v[22:25], off nt
	v_lshlrev_b32_e32 v6, 11, v6
	v_lshl_add_u64 v[26:27], v[64:65], 0, v[6:7]
	v_cvt_pk_bf16_f32 v22, v29, v31
	v_cvt_pk_bf16_f32 v23, v33, v35
	v_cvt_pk_bf16_f32 v24, v37, v39
	v_cvt_pk_bf16_f32 v25, v41, v67
	ds_read2_b32 v[28:29], v42 offset0:48 offset1:56
	ds_read2_b32 v[30:31], v42 offset0:113 offset1:121
	ds_read2_b32 v[32:33], v42 offset0:178 offset1:186
	ds_read2_b32 v[34:35], v42 offset0:243 offset1:251
	ds_read2_b32 v[36:37], v69 offset0:52 offset1:60
	ds_read2_b32 v[38:39], v69 offset0:117 offset1:125
	ds_read2_b32 v[40:41], v69 offset0:182 offset1:190
	ds_read2_b32 v[66:67], v69 offset0:247 offset1:255
	v_or_b32_e32 v6, v68, v48
	v_lshlrev_b32_e32 v6, 11, v6
	global_store_dwordx4 v[26:27], v[22:25], off nt
	v_lshl_add_u64 v[26:27], v[64:65], 0, v[6:7]
	v_or_b32_e32 v6, v68, v49
	s_waitcnt lgkmcnt(6)
	v_cvt_pk_bf16_f32 v22, v28, v30
	s_waitcnt lgkmcnt(4)
	v_cvt_pk_bf16_f32 v23, v32, v34
	s_waitcnt lgkmcnt(2)
	v_cvt_pk_bf16_f32 v24, v36, v38
	s_waitcnt lgkmcnt(0)
	v_cvt_pk_bf16_f32 v25, v40, v66
	v_lshlrev_b32_e32 v6, 11, v6
	global_store_dwordx4 v[26:27], v[22:25], off nt
	v_lshl_add_u64 v[26:27], v[64:65], 0, v[6:7]
	s_nop 0
	v_cvt_pk_bf16_f32 v22, v29, v31
	v_cvt_pk_bf16_f32 v23, v33, v35
	v_cvt_pk_bf16_f32 v24, v37, v39
	v_cvt_pk_bf16_f32 v25, v41, v67
	global_store_dwordx4 v[26:27], v[22:25], off nt
	s_waitcnt lgkmcnt(0)

; #define LAS __attribute__((address_space(3)))
; __device__ __forceinline__ unsigned pk2(float lo, float hi) { f32x2_t v = {lo, hi}; bf16x2_t b = __builtin_convertvector(v, bf16x2_t); return __builtin_bit_cast(unsigned, b); }
; #define LDS_WAIT() asm volatile("s_waitcnt lgkmcnt(0)" ::: "memory")
; __device__ __forceinline__ void tr_item(const float* W, int ldw, int src_c0, bf16_t* WT, int K, int n0, int k0, LAS float* scr, int lane, bool nt) {
;     const int r4 = lane >> 4, c4 = (lane & 15) * 4;
; #pragma unroll 8
;     for (int it = 0; it < 16; ++it) { const int kk = 4 * it + r4; const f32x4 v = __builtin_nontemporal_load((const f32x4*)(W + (size_t)(k0 + kk) * ldw + src_c0 + c4));
;         LAS float* d = scr + kk * 65 + c4; d[0] = v[0]; d[1] = v[1]; d[2] = v[2]; d[3] = v[3]; }
;     LDS_WAIT();
;     const int c = lane & 7;
; #pragma unroll
;     for (int j = 0; j < 8; ++j) { const int n = (lane >> 3) + 8 * j; const LAS float* s = scr + (8 * c) * 65 + n;
;         u32x4 o; o.x = pk2(s[0 * 65], s[1 * 65]); o.y = pk2(s[2 * 65], s[3 * 65]); o.z = pk2(s[4 * 65], s[5 * 65]); o.w = pk2(s[6 * 65], s[7 * 65]);
;         if (nt) __builtin_nontemporal_store(o, (u32x4*)(WT + (size_t)(n0 + n) * K + k0 + 8 * c)); else *(u32x4*)(WT + (size_t)(n0 + n) * K + k0 + 8 * c) = o; }
;     LDS_WAIT();
; }
.LBB0_34:
	v_lshl_add_u64 v[64:65], v[38:39], 0, s[38:39]
	v_lshl_add_u64 v[68:69], v[36:37], 0, s[38:39]
	v_lshl_add_u64 v[72:73], v[34:35], 0, s[38:39]
	v_lshl_add_u64 v[76:77], v[32:33], 0, s[38:39]
	v_lshl_add_u64 v[80:81], v[30:31], 0, s[38:39]
	v_lshl_add_u64 v[84:85], v[28:29], 0, s[38:39]
	v_lshl_add_u64 v[88:89], v[26:27], 0, s[38:39]
	v_lshl_add_u64 v[92:93], v[24:25], 0, s[38:39]
	global_load_dwordx4 v[64:67], v[64:65], off nt
	s_nop 0
	global_load_dwordx4 v[68:71], v[68:69], off nt
	s_nop 0
	global_load_dwordx4 v[72:75], v[72:73], off nt
	s_nop 0
	global_load_dwordx4 v[76:79], v[76:77], off nt
	s_nop 0
	global_load_dwordx4 v[80:83], v[80:81], off nt
	s_nop 0
	global_load_dwordx4 v[84:87], v[84:85], off nt
	s_nop 0
	global_load_dwordx4 v[88:91], v[88:89], off nt
	s_nop 0
	global_load_dwordx4 v[92:95], v[92:93], off nt
	s_add_u32 s38, s38, 0x40000
	s_addc_u32 s39, s39, 0
	v_add_u32_e32 v96, 0x410, v6
	v_add_u32_e32 v97, 0x418, v6
	v_add_u32_e32 v98, 0x820, v6
	v_add_u32_e32 v99, 0x828, v6
	v_add_u32_e32 v100, 0xc30, v6
	v_add_u32_e32 v101, 0xc38, v6
	v_add_u32_e32 v102, 0x1040, v6
	v_add_u32_e32 v103, 0x1048, v6
	v_add_u32_e32 v104, 0x1450, v6
	v_add_u32_e32 v105, 0x1458, v6
	v_add_u32_e32 v106, 0x1860, v6
	v_add_u32_e32 v107, 0x1868, v6
	v_add_u32_e32 v108, 0x1c70, v6
	v_add_u32_e32 v109, 0x1c78, v6
	s_cmp_lg_u32 s38, 0x80000
	s_waitcnt vmcnt(7)
	ds_write2_b32 v6, v64, v65 offset1:1
	ds_write2_b32 v6, v66, v67 offset0:2 offset1:3
	s_waitcnt vmcnt(6)
	ds_write2_b32 v96, v68, v69 offset1:1
	ds_write2_b32 v97, v70, v71 offset1:1
	s_waitcnt vmcnt(5)
	ds_write2_b32 v98, v72, v73 offset1:1
	ds_write2_b32 v99, v74, v75 offset1:1
	s_waitcnt vmcnt(4)
	ds_write2_b32 v100, v76, v77 offset1:1
	ds_write2_b32 v101, v78, v79 offset1:1
	s_waitcnt vmcnt(3)
	ds_write2_b32 v102, v80, v81 offset1:1
	ds_write2_b32 v103, v82, v83 offset1:1
	s_waitcnt vmcnt(2)
	ds_write2_b32 v104, v84, v85 offset1:1
	ds_write2_b32 v105, v86, v87 offset1:1
	s_waitcnt vmcnt(1)
	ds_write2_b32 v106, v88, v89 offset1:1
	ds_write2_b32 v107, v90, v91 offset1:1
	s_waitcnt vmcnt(0)
	ds_write2_b32 v108, v92, v93 offset1:1
	ds_write2_b32 v109, v94, v95 offset1:1
	v_add_u32_e32 v6, 0x2080, v6
	s_cbranch_scc1 .LBB0_34
	v_lshlrev_b32_e32 v6, 6, v40
	s_waitcnt lgkmcnt(0)
	v_add_u32_e32 v69, 0x400, v42
	v_lshlrev_b64 v[22:23], 22, v[22:23]
	v_and_b32_e32 v68, 0x7c0, v6
	v_lshlrev_b32_e32 v6, 1, v41
	ds_read2_b32 v[26:27], v42 offset0:65 offset1:73
	ds_read2_b32 v[28:29], v42 offset1:8
	ds_read2_b32 v[30:31], v42 offset0:130 offset1:138
	ds_read2_b32 v[32:33], v42 offset0:195 offset1:203
	ds_read2_b32 v[34:35], v69 offset0:4 offset1:12
	ds_read2_b32 v[36:37], v69 offset0:69 offset1:77
	ds_read2_b32 v[38:39], v69 offset0:134 offset1:142
	ds_read2_b32 v[40:41], v69 offset0:199 offset1:207
	v_lshl_add_u64 v[22:23], s[20:21], 0, v[22:23]
	v_lshl_add_u64 v[22:23], v[22:23], 0, v[6:7]
	v_lshlrev_b32_e32 v6, 1, v4
	v_lshl_add_u64 v[64:65], v[22:23], 0, v[6:7]
	v_or_b32_e32 v6, v68, v5
	v_lshlrev_b32_e32 v6, 11, v6
	s_waitcnt lgkmcnt(6)
	v_cvt_pk_bf16_f32 v22, v28, v26
	s_waitcnt lgkmcnt(4)
	v_cvt_pk_bf16_f32 v23, v30, v32
	s_waitcnt lgkmcnt(2)
	v_cvt_pk_bf16_f32 v24, v34, v36
	s_waitcnt lgkmcnt(0)
	v_cvt_pk_bf16_f32 v25, v38, v40
	v_lshl_add_u64 v[66:67], v[64:65], 0, v[6:7]
	global_store_dwordx4 v[66:67], v[22:25], off nt
	v_or_b32_e32 v6, v68, v43
	v_lshlrev_b32_e32 v6, 11, v6
	v_cvt_pk_bf16_f32 v22, v29, v27
	v_cvt_pk_bf16_f32 v23, v31, v33
	v_cvt_pk_bf16_f32 v24, v35, v37
	v_cvt_pk_bf16_f32 v25, v39, v41
	ds_read2_b32 v[28:29], v42 offset0:81 offset1:89
	ds_read2_b32 v[30:31], v42 offset0:16 offset1:24
	ds_read2_b32 v[32:33], v42 offset0:146 offset1:154
	ds_read2_b32 v[34:35], v42 offset0:211 offset1:219
	ds_read2_b32 v[36:37], v69 offset0:20 offset1:28
	ds_read2_b32 v[38:39], v69 offset0:85 offset1:93
	ds_read2_b32 v[40:41], v69 offset0:150 offset1:158
	ds_read2_b32 v[66:67], v69 offset0:215 offset1:223
	v_lshl_add_u64 v[26:27], v[64:65], 0, v[6:7]
	v_or_b32_e32 v6, v68, v44
	v_lshlrev_b32_e32 v6, 11, v6
	global_store_dwordx4 v[26:27], v[22:25], off nt
	v_lshl_add_u64 v[26:27], v[64:65], 0, v[6:7]
	v_or_b32_e32 v6, v68, v45
	s_waitcnt lgkmcnt(6)
	v_cvt_pk_bf16_f32 v22, v30, v28
	s_waitcnt lgkmcnt(4)
	v_cvt_pk_bf16_f32 v23, v32, v34
	s_waitcnt lgkmcnt(2)
	v_cvt_pk_bf16_f32 v24, v36, v38
	s_waitcnt lgkmcnt(0)
	v_cvt_pk_bf16_f32 v25, v40, v66
	global_store_dwordx4 v[26:27], v[22:25], off nt
	v_lshlrev_b32_e32 v6, 11, v6
	v_lshl_add_u64 v[26:27], v[64:65], 0, v[6:7]
	v_cvt_pk_bf16_f32 v22, v31, v29
	v_cvt_pk_bf16_f32 v23, v33, v35
	v_cvt_pk_bf16_f32 v24, v37, v39
	v_cvt_pk_bf16_f32 v25, v41, v67
	ds_read2_b32 v[28:29], v42 offset0:32 offset1:40
	ds_read2_b32 v[30:31], v42 offset0:97 offset1:105
	ds_read2_b32 v[32:33], v42 offset0:162 offset1:170
	ds_read2_b32 v[34:35], v42 offset0:227 offset1:235
	ds_read2_b32 v[36:37], v69 offset0:36 offset1:44
	ds_read2_b32 v[38:39], v69 offset0:101 offset1:109
	ds_read2_b32 v[40:41], v69 offset0:166 offset1:174
	ds_read2_b32 v[66:67], v69 offset0:231 offset1:239
	v_or_b32_e32 v6, v68, v46
	v_lshlrev_b32_e32 v6, 11, v6
	global_store_dwordx4 v[26:27], v[22:25], off nt
	v_lshl_add_u64 v[26:27], v[64:65], 0, v[6:7]
	v_or_b32_e32 v6, v68, v47
	s_waitcnt lgkmcnt(6)
	v_cvt_pk_bf16_f32 v22, v28, v30
	s_waitcnt lgkmcnt(4)
	v_cvt_pk_bf16_f32 v23, v32, v34
	s_waitcnt lgkmcnt(2)
	v_cvt_pk_bf16_f32 v24, v36, v38
	s_waitcnt lgkmcnt(0)
	v_cvt_pk_bf16_f32 v25, v40, v66
	global_store_dwordx4 v[26:27], v[22:25], off nt
	v_lshlrev_b32_e32 v6, 11, v6
	v_lshl_add_u64 v[26:27], v[64:65], 0, v[6:7]
	v_cvt_pk_bf16_f32 v22, v29, v31
	v_cvt_pk_bf16_f32 v23, v33, v35
	v_cvt_pk_bf16_f32 v24, v37, v39
	v_cvt_pk_bf16_f32 v25, v41, v67
	ds_read2_b32 v[28:29], v42 offset0:48 offset1:56
	ds_read2_b32 v[30:31], v42 offset0:113 offset1:121
	ds_read2_b32 v[32:33], v42 offset0:178 offset1:186
	ds_read2_b32 v[34:35], v42 offset0:243 offset1:251
	ds_read2_b32 v[36:37], v69 offset0:52 offset1:60
	ds_read2_b32 v[38:39], v69 offset0:117 offset1:125
	ds_read2_b32 v[40:41], v69 offset0:182 offset1:190
	ds_read2_b32 v[66:67], v69 offset0:247 offset1:255
	v_or_b32_e32 v6, v68, v48
	v_lshlrev_b32_e32 v6, 11, v6
	global_store_dwordx4 v[26:27], v[22:25], off nt
	v_lshl_add_u64 v[26:27], v[64:65], 0, v[6:7]
	v_or_b32_e32 v6, v68, v49
	s_waitcnt lgkmcnt(6)
	v_cvt_pk_bf16_f32 v22, v28, v30
	s_waitcnt lgkmcnt(4)
	v_cvt_pk_bf16_f32 v23, v32, v34
	s_waitcnt lgkmcnt(2)
	v_cvt_pk_bf16_f32 v24, v36, v38
	s_waitcnt lgkmcnt(0)
	v_cvt_pk_bf16_f32 v25, v40, v66
	v_lshlrev_b32_e32 v6, 11, v6
	global_store_dwordx4 v[26:27], v[22:25], off nt
	v_lshl_add_u64 v[26:27], v[64:65], 0, v[6:7]
	s_nop 0
	v_cvt_pk_bf16_f32 v22, v29, v31
	v_cvt_pk_bf16_f32 v23, v33, v35
	v_cvt_pk_bf16_f32 v24, v37, v39
	v_cvt_pk_bf16_f32 v25, v41, v67
	global_store_dwordx4 v[26:27], v[22:25], off nt
	s_waitcnt lgkmcnt(0)

; #define LAS __attribute__((address_space(3)))
; __device__ __forceinline__ unsigned pk2(float lo, float hi) { f32x2_t v = {lo, hi}; bf16x2_t b = __builtin_convertvector(v, bf16x2_t); return __builtin_bit_cast(unsigned, b); }
; #define LDS_WAIT() asm volatile("s_waitcnt lgkmcnt(0)" ::: "memory")
; __device__ __forceinline__ void tr_item(const float* W, int ldw, int src_c0, bf16_t* WT, int K, int n0, int k0, LAS float* scr, int lane, bool nt) {
;     const int r4 = lane >> 4, c4 = (lane & 15) * 4;
; #pragma unroll 8
;     for (int it = 0; it < 16; ++it) { const int kk = 4 * it + r4; const f32x4 v = __builtin_nontemporal_load((const f32x4*)(W + (size_t)(k0 + kk) * ldw + src_c0 + c4));
;         LAS float* d = scr + kk * 65 + c4; d[0] = v[0]; d[1] = v[1]; d[2] = v[2]; d[3] = v[3]; }
;     LDS_WAIT();
;     const int c = lane & 7;
; #pragma unroll
;     for (int j = 0; j < 8; ++j) { const int n = (lane >> 3) + 8 * j; const LAS float* s = scr + (8 * c) * 65 + n;
;         u32x4 o; o.x = pk2(s[0 * 65], s[1 * 65]); o.y = pk2(s[2 * 65], s[3 * 65]); o.z = pk2(s[4 * 65], s[5 * 65]); o.w = pk2(s[6 * 65], s[7 * 65]);
;         if (nt) __builtin_nontemporal_store(o, (u32x4*)(WT + (size_t)(n0 + n) * K + k0 + 8 * c)); else *(u32x4*)(WT + (size_t)(n0 + n) * K + k0 + 8 * c) = o; }
;     LDS_WAIT();
; }
.LBB0_39:
	v_lshl_add_u64 v[64:65], v[38:39], 0, s[36:37]
	v_lshl_add_u64 v[68:69], v[36:37], 0, s[36:37]
	v_lshl_add_u64 v[72:73], v[34:35], 0, s[36:37]
	v_lshl_add_u64 v[76:77], v[32:33], 0, s[36:37]
	v_lshl_add_u64 v[80:81], v[30:31], 0, s[36:37]
	v_lshl_add_u64 v[84:85], v[28:29], 0, s[36:37]
	v_lshl_add_u64 v[88:89], v[26:27], 0, s[36:37]
	v_lshl_add_u64 v[92:93], v[24:25], 0, s[36:37]
	global_load_dwordx4 v[64:67], v[64:65], off nt
	s_nop 0
	global_load_dwordx4 v[68:71], v[68:69], off nt
	s_nop 0
	global_load_dwordx4 v[72:75], v[72:73], off nt
	s_nop 0
	global_load_dwordx4 v[76:79], v[76:77], off nt
	s_nop 0
	global_load_dwordx4 v[80:83], v[80:81], off nt
	s_nop 0
	global_load_dwordx4 v[84:87], v[84:85], off nt
	s_nop 0
	global_load_dwordx4 v[88:91], v[88:89], off nt
	s_nop 0
	global_load_dwordx4 v[92:95], v[92:93], off nt
	s_add_u32 s36, s36, 0x40000
	s_addc_u32 s37, s37, 0
	v_add_u32_e32 v96, 0x410, v6
	v_add_u32_e32 v97, 0x418, v6
	v_add_u32_e32 v98, 0x820, v6
	v_add_u32_e32 v99, 0x828, v6
	v_add_u32_e32 v100, 0xc30, v6
	v_add_u32_e32 v101, 0xc38, v6
	v_add_u32_e32 v102, 0x1040, v6
	v_add_u32_e32 v103, 0x1048, v6
	v_add_u32_e32 v104, 0x1450, v6
	v_add_u32_e32 v105, 0x1458, v6
	v_add_u32_e32 v106, 0x1860, v6
	v_add_u32_e32 v107, 0x1868, v6
	v_add_u32_e32 v108, 0x1c70, v6
	v_add_u32_e32 v109, 0x1c78, v6
	s_cmp_lg_u32 s36, 0x80000
	s_waitcnt vmcnt(7)
	ds_write2_b32 v6, v64, v65 offset1:1
	ds_write2_b32 v6, v66, v67 offset0:2 offset1:3
	s_waitcnt vmcnt(6)
	ds_write2_b32 v96, v68, v69 offset1:1
	ds_write2_b32 v97, v70, v71 offset1:1
	s_waitcnt vmcnt(5)
	ds_write2_b32 v98, v72, v73 offset1:1
	ds_write2_b32 v99, v74, v75 offset1:1
	s_waitcnt vmcnt(4)
	ds_write2_b32 v100, v76, v77 offset1:1
	ds_write2_b32 v101, v78, v79 offset1:1
	s_waitcnt vmcnt(3)
	ds_write2_b32 v102, v80, v81 offset1:1
	ds_write2_b32 v103, v82, v83 offset1:1
	s_waitcnt vmcnt(2)
	ds_write2_b32 v104, v84, v85 offset1:1
	ds_write2_b32 v105, v86, v87 offset1:1
	s_waitcnt vmcnt(1)
	ds_write2_b32 v106, v88, v89 offset1:1
	ds_write2_b32 v107, v90, v91 offset1:1
	s_waitcnt vmcnt(0)
	ds_write2_b32 v108, v92, v93 offset1:1
	ds_write2_b32 v109, v94, v95 offset1:1
	v_add_u32_e32 v6, 0x2080, v6
	s_cbranch_scc1 .LBB0_39
	v_lshlrev_b32_e32 v6, 6, v40
	s_waitcnt lgkmcnt(0)
	v_add_u32_e32 v69, 0x400, v42
	v_lshlrev_b64 v[22:23], 22, v[22:23]
	v_and_b32_e32 v68, 0x7c0, v6
	v_lshlrev_b32_e32 v6, 1, v41
	ds_read2_b32 v[26:27], v42 offset0:65 offset1:73
	ds_read2_b32 v[28:29], v42 offset1:8
	ds_read2_b32 v[30:31], v42 offset0:130 offset1:138
	ds_read2_b32 v[32:33], v42 offset0:195 offset1:203
	ds_read2_b32 v[34:35], v69 offset0:4 offset1:12
	ds_read2_b32 v[36:37], v69 offset0:69 offset1:77
	ds_read2_b32 v[38:39], v69 offset0:134 offset1:142
	ds_read2_b32 v[40:41], v69 offset0:199 offset1:207
	v_lshl_add_u64 v[22:23], s[26:27], 0, v[22:23]
	v_lshl_add_u64 v[22:23], v[22:23], 0, v[6:7]
	v_lshlrev_b32_e32 v6, 1, v4
	v_lshl_add_u64 v[64:65], v[22:23], 0, v[6:7]
	v_or_b32_e32 v6, v68, v5
	v_lshlrev_b32_e32 v6, 11, v6
	s_waitcnt lgkmcnt(6)
	v_cvt_pk_bf16_f32 v22, v28, v26
	s_waitcnt lgkmcnt(4)
	v_cvt_pk_bf16_f32 v23, v30, v32
	s_waitcnt lgkmcnt(2)
	v_cvt_pk_bf16_f32 v24, v34, v36
	s_waitcnt lgkmcnt(0)
	v_cvt_pk_bf16_f32 v25, v38, v40
	v_lshl_add_u64 v[66:67], v[64:65], 0, v[6:7]
	global_store_dwordx4 v[66:67], v[22:25], off nt
	v_or_b32_e32 v6, v68, v43
	v_lshlrev_b32_e32 v6, 11, v6
	v_cvt_pk_bf16_f32 v22, v29, v27
	v_cvt_pk_bf16_f32 v23, v31, v33
	v_cvt_pk_bf16_f32 v24, v35, v37
	v_cvt_pk_bf16_f32 v25, v39, v41
	ds_read2_b32 v[28:29], v42 offset0:81 offset1:89
	ds_read2_b32 v[30:31], v42 offset0:16 offset1:24
	ds_read2_b32 v[32:33], v42 offset0:146 offset1:154
	ds_read2_b32 v[34:35], v42 offset0:211 offset1:219
	ds_read2_b32 v[36:37], v69 offset0:20 offset1:28
	ds_read2_b32 v[38:39], v69 offset0:85 offset1:93
	ds_read2_b32 v[40:41], v69 offset0:150 offset1:158
	ds_read2_b32 v[66:67], v69 offset0:215 offset1:223
	v_lshl_add_u64 v[26:27], v[64:65], 0, v[6:7]
	v_or_b32_e32 v6, v68, v44
	v_lshlrev_b32_e32 v6, 11, v6
	global_store_dwordx4 v[26:27], v[22:25], off nt
	v_lshl_add_u64 v[26:27], v[64:65], 0, v[6:7]
	v_or_b32_e32 v6, v68, v45
	s_waitcnt lgkmcnt(6)
	v_cvt_pk_bf16_f32 v22, v30, v28
	s_waitcnt lgkmcnt(4)
	v_cvt_pk_bf16_f32 v23, v32, v34
	s_waitcnt lgkmcnt(2)
	v_cvt_pk_bf16_f32 v24, v36, v38
	s_waitcnt lgkmcnt(0)
	v_cvt_pk_bf16_f32 v25, v40, v66
	global_store_dwordx4 v[26:27], v[22:25], off nt
	v_lshlrev_b32_e32 v6, 11, v6
	v_lshl_add_u64 v[26:27], v[64:65], 0, v[6:7]
	v_cvt_pk_bf16_f32 v22, v31, v29
	v_cvt_pk_bf16_f32 v23, v33, v35
	v_cvt_pk_bf16_f32 v24, v37, v39
	v_cvt_pk_bf16_f32 v25, v41, v67
	ds_read2_b32 v[28:29], v42 offset0:32 offset1:40
	ds_read2_b32 v[30:31], v42 offset0:97 offset1:105
	ds_read2_b32 v[32:33], v42 offset0:162 offset1:170
	ds_read2_b32 v[34:35], v42 offset0:227 offset1:235
	ds_read2_b32 v[36:37], v69 offset0:36 offset1:44
	ds_read2_b32 v[38:39], v69 offset0:101 offset1:109
	ds_read2_b32 v[40:41], v69 offset0:166 offset1:174
	ds_read2_b32 v[66:67], v69 offset0:231 offset1:239
	v_or_b32_e32 v6, v68, v46
	v_lshlrev_b32_e32 v6, 11, v6
	global_store_dwordx4 v[26:27], v[22:25], off nt
	v_lshl_add_u64 v[26:27], v[64:65], 0, v[6:7]
	v_or_b32_e32 v6, v68, v47
	s_waitcnt lgkmcnt(6)
	v_cvt_pk_bf16_f32 v22, v28, v30
	s_waitcnt lgkmcnt(4)
	v_cvt_pk_bf16_f32 v23, v32, v34
	s_waitcnt lgkmcnt(2)
	v_cvt_pk_bf16_f32 v24, v36, v38
	s_waitcnt lgkmcnt(0)
	v_cvt_pk_bf16_f32 v25, v40, v66
	global_store_dwordx4 v[26:27], v[22:25], off nt
	v_lshlrev_b32_e32 v6, 11, v6
	v_lshl_add_u64 v[26:27], v[64:65], 0, v[6:7]
	v_cvt_pk_bf16_f32 v22, v29, v31
	v_cvt_pk_bf16_f32 v23, v33, v35
	v_cvt_pk_bf16_f32 v24, v37, v39
	v_cvt_pk_bf16_f32 v25, v41, v67
	ds_read2_b32 v[28:29], v42 offset0:48 offset1:56
	ds_read2_b32 v[30:31], v42 offset0:113 offset1:121
	ds_read2_b32 v[32:33], v42 offset0:178 offset1:186
	ds_read2_b32 v[34:35], v42 offset0:243 offset1:251
	ds_read2_b32 v[36:37], v69 offset0:52 offset1:60
	ds_read2_b32 v[38:39], v69 offset0:117 offset1:125
	ds_read2_b32 v[40:41], v69 offset0:182 offset1:190
	ds_read2_b32 v[66:67], v69 offset0:247 offset1:255
	v_or_b32_e32 v6, v68, v48
	v_lshlrev_b32_e32 v6, 11, v6
	global_store_dwordx4 v[26:27], v[22:25], off nt
	v_lshl_add_u64 v[26:27], v[64:65], 0, v[6:7]
	v_or_b32_e32 v6, v68, v49
	s_waitcnt lgkmcnt(6)
	v_cvt_pk_bf16_f32 v22, v28, v30
	s_waitcnt lgkmcnt(4)
	v_cvt_pk_bf16_f32 v23, v32, v34
	s_waitcnt lgkmcnt(2)
	v_cvt_pk_bf16_f32 v24, v36, v38
	s_waitcnt lgkmcnt(0)
	v_cvt_pk_bf16_f32 v25, v40, v66
	v_lshlrev_b32_e32 v6, 11, v6
	global_store_dwordx4 v[26:27], v[22:25], off nt
	v_lshl_add_u64 v[26:27], v[64:65], 0, v[6:7]
	s_nop 0
	v_cvt_pk_bf16_f32 v22, v29, v31
	v_cvt_pk_bf16_f32 v23, v33, v35
	v_cvt_pk_bf16_f32 v24, v37, v39
	v_cvt_pk_bf16_f32 v25, v41, v67
	global_store_dwordx4 v[26:27], v[22:25], off nt
	s_waitcnt lgkmcnt(0)

; #define LAS __attribute__((address_space(3)))
; __device__ __forceinline__ void tr_item(const float* W, int ldw, int src_c0, bf16_t* WT, int K, int n0, int k0, LAS float* scr, int lane, bool nt) {
;     ...
; #pragma unroll 8
;     for (int it = 0; it < 16; ++it) { const int kk = 4 * it + r4; const f32x4 v = __builtin_nontemporal_load((const f32x4*)(W + (size_t)(k0 + kk) * ldw + src_c0 + c4));
;         LAS float* d = scr + kk * 65 + c4; d[0] = v[0]; d[1] = v[1]; d[2] = v[2]; d[3] = v[3]; }
.LBB0_44:
	v_lshl_add_u64 v[64:65], v[40:41], 0, s[34:35]
	v_lshl_add_u64 v[68:69], v[38:39], 0, s[34:35]
	v_lshl_add_u64 v[72:73], v[36:37], 0, s[34:35]
	v_lshl_add_u64 v[76:77], v[34:35], 0, s[34:35]
	v_lshl_add_u64 v[80:81], v[32:33], 0, s[34:35]
	v_lshl_add_u64 v[84:85], v[30:31], 0, s[34:35]
	v_lshl_add_u64 v[88:89], v[28:29], 0, s[34:35]
	v_lshl_add_u64 v[92:93], v[26:27], 0, s[34:35]
	global_load_dwordx4 v[64:67], v[64:65], off nt
	s_nop 0
	global_load_dwordx4 v[68:71], v[68:69], off nt
	s_nop 0
	global_load_dwordx4 v[72:75], v[72:73], off nt
	s_nop 0
	global_load_dwordx4 v[76:79], v[76:77], off nt
	s_nop 0
	global_load_dwordx4 v[80:83], v[80:81], off nt
	s_nop 0
	global_load_dwordx4 v[84:87], v[84:85], off nt
	s_nop 0
	global_load_dwordx4 v[88:91], v[88:89], off nt
	s_nop 0
	global_load_dwordx4 v[92:95], v[92:93], off nt
	s_add_u32 s34, s34, 0x220400
	s_addc_u32 s35, s35, 0
	v_add_u32_e32 v96, 0x410, v6
	v_add_u32_e32 v97, 0x418, v6
	v_add_u32_e32 v98, 0x820, v6
	v_add_u32_e32 v99, 0x828, v6
	v_add_u32_e32 v100, 0xc30, v6
	v_add_u32_e32 v101, 0xc38, v6
	v_add_u32_e32 v102, 0x1040, v6
	v_add_u32_e32 v103, 0x1048, v6
	v_add_u32_e32 v104, 0x1450, v6
	v_add_u32_e32 v105, 0x1458, v6
	v_add_u32_e32 v106, 0x1860, v6
	v_add_u32_e32 v107, 0x1868, v6
	v_add_u32_e32 v108, 0x1c70, v6
	v_add_u32_e32 v109, 0x1c78, v6
	s_cmp_lg_u32 s34, 0x440800
	s_waitcnt vmcnt(7)
	ds_write2_b32 v6, v64, v65 offset1:1
	ds_write2_b32 v6, v66, v67 offset0:2 offset1:3
	s_waitcnt vmcnt(6)
	ds_write2_b32 v96, v68, v69 offset1:1
	ds_write2_b32 v97, v70, v71 offset1:1
	s_waitcnt vmcnt(5)
	ds_write2_b32 v98, v72, v73 offset1:1
	ds_write2_b32 v99, v74, v75 offset1:1
	s_waitcnt vmcnt(4)
	ds_write2_b32 v100, v76, v77 offset1:1
	ds_write2_b32 v101, v78, v79 offset1:1
	s_waitcnt vmcnt(3)
	ds_write2_b32 v102, v80, v81 offset1:1
	ds_write2_b32 v103, v82, v83 offset1:1
	s_waitcnt vmcnt(2)
	ds_write2_b32 v104, v84, v85 offset1:1
	ds_write2_b32 v105, v86, v87 offset1:1
	s_waitcnt vmcnt(1)
	ds_write2_b32 v106, v88, v89 offset1:1
	ds_write2_b32 v107, v90, v91 offset1:1
	s_waitcnt vmcnt(0)
	ds_write2_b32 v108, v92, v93 offset1:1
	ds_write2_b32 v109, v94, v95 offset1:1
	v_add_u32_e32 v6, 0x2080, v6
	s_cbranch_scc1 .LBB0_44
; #define LAS __attribute__((address_space(3)))
; __device__ __forceinline__ unsigned pk2(float lo, float hi) { f32x2_t v = {lo, hi}; bf16x2_t b = __builtin_convertvector(v, bf16x2_t); return __builtin_bit_cast(unsigned, b); }
; #define LDS_WAIT() asm volatile("s_waitcnt lgkmcnt(0)" ::: "memory")
; __device__ __forceinline__ void tr_item(const float* W, int ldw, int src_c0, bf16_t* WT, int K, int n0, int k0, LAS float* scr, int lane, bool nt) {
;     ...
;     LDS_WAIT();
;     const int c = lane & 7;
; #pragma unroll
;     for (int j = 0; j < 8; ++j) { const int n = (lane >> 3) + 8 * j; const LAS float* s = scr + (8 * c) * 65 + n;
;         u32x4 o; o.x = pk2(s[0 * 65], s[1 * 65]); o.y = pk2(s[2 * 65], s[3 * 65]); o.z = pk2(s[4 * 65], s[5 * 65]); o.w = pk2(s[6 * 65], s[7 * 65]);
;         if (nt) __builtin_nontemporal_store(o, (u32x4*)(WT + (size_t)(n0 + n) * K + k0 + 8 * c)); else *(u32x4*)(WT + (size_t)(n0 + n) * K + k0 + 8 * c) = o; }
;     LDS_WAIT();
; }
	v_mov_b64_e32 v[26:27], s[4:5]
	v_mad_i64_i32 v[26:27], s[34:35], v22, s53, v[26:27]
	s_waitcnt lgkmcnt(0)
	v_add_u32_e32 v22, 0x400, v42
	ds_read2_b32 v[28:29], v42 offset0:65 offset1:73
	ds_read2_b32 v[30:31], v42 offset1:8
	ds_read2_b32 v[32:33], v42 offset0:130 offset1:138
	ds_read2_b32 v[34:35], v42 offset0:195 offset1:203
	ds_read2_b32 v[36:37], v22 offset0:4 offset1:12
	ds_read2_b32 v[38:39], v22 offset0:69 offset1:77
	ds_read2_b32 v[40:41], v22 offset0:134 offset1:142
	ds_read2_b32 v[64:65], v22 offset0:199 offset1:207
	v_or_b32_e32 v68, v23, v5
	v_lshl_add_u64 v[24:25], v[24:25], 1, v[26:27]
	v_lshlrev_b32_e32 v6, 1, v4
	v_ashrrev_i32_e32 v69, 31, v68
	v_lshl_add_u64 v[66:67], v[24:25], 0, v[6:7]
	v_lshlrev_b64 v[68:69], 12, v[68:69]
	s_waitcnt lgkmcnt(6)
	v_cvt_pk_bf16_f32 v24, v30, v28
	s_waitcnt lgkmcnt(4)
	v_cvt_pk_bf16_f32 v25, v32, v34
	s_waitcnt lgkmcnt(2)
	v_cvt_pk_bf16_f32 v26, v36, v38
	s_waitcnt lgkmcnt(0)
	v_cvt_pk_bf16_f32 v27, v40, v64
	v_lshl_add_u64 v[68:69], v[66:67], 0, v[68:69]
	v_or_b32_e32 v28, v23, v43
	global_store_dwordx4 v[68:69], v[24:27], off nt
	s_nop 1
	v_cvt_pk_bf16_f32 v24, v31, v29
	v_ashrrev_i32_e32 v29, 31, v28
	v_cvt_pk_bf16_f32 v25, v33, v35
	v_cvt_pk_bf16_f32 v26, v37, v39
	v_cvt_pk_bf16_f32 v27, v41, v65
	v_lshlrev_b64 v[28:29], 12, v[28:29]
	ds_read2_b32 v[30:31], v42 offset0:81 offset1:89
	ds_read2_b32 v[32:33], v42 offset0:16 offset1:24
	ds_read2_b32 v[34:35], v42 offset0:146 offset1:154
	ds_read2_b32 v[36:37], v42 offset0:211 offset1:219
	ds_read2_b32 v[38:39], v22 offset0:20 offset1:28
	ds_read2_b32 v[40:41], v22 offset0:85 offset1:93
	ds_read2_b32 v[64:65], v22 offset0:150 offset1:158
	ds_read2_b32 v[68:69], v22 offset0:215 offset1:223
	v_lshl_add_u64 v[28:29], v[66:67], 0, v[28:29]
	global_store_dwordx4 v[28:29], v[24:27], off nt
	v_or_b32_e32 v28, v23, v44
	v_ashrrev_i32_e32 v29, 31, v28
	v_lshlrev_b64 v[28:29], 12, v[28:29]
	s_waitcnt lgkmcnt(6)
	v_cvt_pk_bf16_f32 v24, v32, v30
	s_waitcnt lgkmcnt(4)
	v_cvt_pk_bf16_f32 v25, v34, v36
	s_waitcnt lgkmcnt(2)
	v_cvt_pk_bf16_f32 v26, v38, v40
	s_waitcnt lgkmcnt(0)
	v_cvt_pk_bf16_f32 v27, v64, v68
	v_lshl_add_u64 v[28:29], v[66:67], 0, v[28:29]
	global_store_dwordx4 v[28:29], v[24:27], off nt
	v_or_b32_e32 v28, v23, v45
	v_ashrrev_i32_e32 v29, 31, v28
	v_cvt_pk_bf16_f32 v24, v33, v31
	v_cvt_pk_bf16_f32 v25, v35, v37
	v_cvt_pk_bf16_f32 v26, v39, v41
	v_cvt_pk_bf16_f32 v27, v65, v69
	v_lshlrev_b64 v[28:29], 12, v[28:29]
	ds_read2_b32 v[30:31], v42 offset0:32 offset1:40
	ds_read2_b32 v[32:33], v42 offset0:97 offset1:105
	ds_read2_b32 v[34:35], v42 offset0:162 offset1:170
	ds_read2_b32 v[36:37], v42 offset0:227 offset1:235
	ds_read2_b32 v[38:39], v22 offset0:36 offset1:44
	ds_read2_b32 v[40:41], v22 offset0:101 offset1:109
	ds_read2_b32 v[64:65], v22 offset0:166 offset1:174
	ds_read2_b32 v[68:69], v22 offset0:231 offset1:239
	v_lshl_add_u64 v[28:29], v[66:67], 0, v[28:29]
	global_store_dwordx4 v[28:29], v[24:27], off nt
	v_or_b32_e32 v28, v23, v46
	v_ashrrev_i32_e32 v29, 31, v28
	v_lshlrev_b64 v[28:29], 12, v[28:29]
	s_waitcnt lgkmcnt(6)
	v_cvt_pk_bf16_f32 v24, v30, v32
	s_waitcnt lgkmcnt(4)
	v_cvt_pk_bf16_f32 v25, v34, v36
	s_waitcnt lgkmcnt(2)
	v_cvt_pk_bf16_f32 v26, v38, v40
	s_waitcnt lgkmcnt(0)
	v_cvt_pk_bf16_f32 v27, v64, v68
	v_lshl_add_u64 v[28:29], v[66:67], 0, v[28:29]
	global_store_dwordx4 v[28:29], v[24:27], off nt
	v_or_b32_e32 v28, v23, v47
	v_ashrrev_i32_e32 v29, 31, v28
	v_cvt_pk_bf16_f32 v24, v31, v33
	v_cvt_pk_bf16_f32 v25, v35, v37
	v_cvt_pk_bf16_f32 v26, v39, v41
	v_cvt_pk_bf16_f32 v27, v65, v69
	v_lshlrev_b64 v[28:29], 12, v[28:29]
	ds_read2_b32 v[30:31], v42 offset0:48 offset1:56
	ds_read2_b32 v[32:33], v42 offset0:113 offset1:121
	ds_read2_b32 v[34:35], v42 offset0:178 offset1:186
	ds_read2_b32 v[36:37], v42 offset0:243 offset1:251
	ds_read2_b32 v[38:39], v22 offset0:52 offset1:60
	ds_read2_b32 v[40:41], v22 offset0:117 offset1:125
	ds_read2_b32 v[64:65], v22 offset0:182 offset1:190
	ds_read2_b32 v[68:69], v22 offset0:247 offset1:255
	v_lshl_add_u64 v[28:29], v[66:67], 0, v[28:29]
	global_store_dwordx4 v[28:29], v[24:27], off nt
	v_or_b32_e32 v28, v23, v48
	v_ashrrev_i32_e32 v29, 31, v28
	v_or_b32_e32 v22, v23, v49
	v_lshlrev_b64 v[28:29], 12, v[28:29]
	v_ashrrev_i32_e32 v23, 31, v22
	s_waitcnt lgkmcnt(6)
	v_cvt_pk_bf16_f32 v24, v30, v32
	s_waitcnt lgkmcnt(4)
	v_cvt_pk_bf16_f32 v25, v34, v36
	s_waitcnt lgkmcnt(2)
	v_cvt_pk_bf16_f32 v26, v38, v40
	s_waitcnt lgkmcnt(0)
	v_cvt_pk_bf16_f32 v27, v64, v68
	v_lshl_add_u64 v[28:29], v[66:67], 0, v[28:29]
	v_lshlrev_b64 v[22:23], 12, v[22:23]
	global_store_dwordx4 v[28:29], v[24:27], off nt
	v_lshl_add_u64 v[22:23], v[66:67], 0, v[22:23]
	s_nop 0
	v_cvt_pk_bf16_f32 v24, v31, v33
	v_cvt_pk_bf16_f32 v25, v35, v37
	v_cvt_pk_bf16_f32 v26, v39, v41
	v_cvt_pk_bf16_f32 v27, v65, v69
	global_store_dwordx4 v[22:23], v[24:27], off nt
	s_waitcnt lgkmcnt(0)
	s_branch .LBB0_7
